# scan y reduction: lane LDS base and the y-row store pointer kept in registers across chunks (hipcc's per-chunk 64-bit address code removed); selector still built per chunk
# speedup vs baseline: 1.0093x; 1.0047x over previous
.LBB0_407:
	s_or_b64 exec, exec, s[12:13]
	v_add_f32_e32 v26, v32, v33
	v_sqrt_f32_e32 v26, v26
	s_waitcnt vmcnt(12)
	v_cvt_f32_f16_sdwa v27, v63 dst_sel:DWORD dst_unused:UNUSED_PAD src0_sel:WORD_1
	v_cvt_f32_f16_sdwa v21, v62 dst_sel:DWORD dst_unused:UNUSED_PAD src0_sel:WORD_1
	v_cvt_f32_f16_e32 v20, v62
	v_max_f32_e32 v26, 0x2b8cbccc, v26
	v_rcp_f32_e32 v26, v26
	v_cvt_f32_f16_e32 v28, v63
	v_cndmask_b32_e64 v29, v27, 1.0, s[0:1]
	s_lshl_b32 s92, s58, 5
	v_pk_mul_f32 v[30:31], v[16:17], v[26:27] op_sel_hi:[1,0]
	v_pk_mul_f32 v[26:27], v[18:19], v[26:27] op_sel_hi:[1,0]
	v_cndmask_b32_e64 v20, v20, 1.0, s[0:1]
	v_cndmask_b32_e64 v28, v28, 1.0, s[0:1]
	v_cndmask_b32_e64 v21, v21, 1.0, s[0:1]
	v_pk_mul_f32 v[14:15], v[14:15], v[30:31]
	v_pk_mul_f32 v[12:13], v[12:13], v[26:27]
	s_lshl_b32 s12, s90, 2
	v_pk_mul_f32 v[18:19], v[28:29], v[30:31] neg_lo:[0,1] neg_hi:[0,1]
	v_pk_mul_f32 v[16:17], v[20:21], v[26:27] neg_lo:[0,1] neg_hi:[0,1]
	v_pk_mul_f32 v[14:15], v[24:25], v[14:15]
	v_pk_mul_f32 v[12:13], v[22:23], v[12:13]
	v_lshl_add_u64 v[84:85], s[60:61], 0, v[42:43]
	v_lshl_add_u64 v[86:87], s[28:29], 0, v[42:43]
	v_lshl_add_u64 v[88:89], s[14:15], 0, v[42:43]
	s_add_u32 s58, s44, s12
	v_mov_b32_e32 v42, v43
	ds_write_b128 v41, v[16:19] offset:12288
	ds_write_b128 v41, v[12:15] offset:16384
	s_addc_u32 s59, s45, 0
	s_mov_b32 s93, 0
	s_mov_b64 s[62:63], 0
	s_mov_b64 s[64:65], -1
	v_mov_b64_e32 v[16:17], v[42:43]
	v_mov_b64_e32 v[18:19], v[42:43]
	v_mov_b64_e32 v[12:13], v[42:43]
	v_mov_b64_e32 v[14:15], v[42:43]
	v_mov_b32_e32 v233, 0
	v_and_b32_e32 v224, 15, v152
	v_mov_b32_e32 v216, 0
	v_mov_b32_e32 v225, 0x3c00
	v_cmp_eq_u32_e32 vcc, 0, v224
	v_mov_b32_e32 v226, 0x3c000000
	s_nop 1
	v_cndmask_b32_e32 v216, v216, v225, vcc
	v_cmp_eq_u32_e32 vcc, 1, v224
	s_nop 1
	v_cndmask_b32_e32 v216, v216, v226, vcc
	s_nop 0
	v_mov_b32_e32 v217, v216
	v_mov_b32_e32 v218, v216
	v_mov_b32_e32 v219, v216
	v_lshrrev_b32_e32 v224, 4, v152
	v_mul_u32_u24_e32 v224, 0x3f0, v224
	v_sub_u32_e32 v222, v105, v224
	v_lshlrev_b32_e32 v232, 1, v40
	v_mov_b32_e32 v229, s11
	v_mov_b32_e32 v227, s33
	v_add_u32_e32 v224, -16, v46
	v_cmp_gt_i32_e32 vcc, s87, v224
	v_add_u32_e32 v226, 0xffffbf80, v224
	v_ashrrev_i32_e32 v225, 31, v224
	v_cndmask_b32_e32 v224, v226, v224, vcc
	v_mov_b32_e32 v226, s10
	v_cndmask_b32_e32 v225, 0, v225, vcc
	v_cndmask_b32_e32 v227, v226, v227, vcc
	v_mov_b32_e32 v226, s3
	v_cndmask_b32_e32 v226, v226, v229, vcc
	v_lshlrev_b64 v[224:225], 11, v[224:225]
	v_lshl_add_u64 v[224:225], v[226:227], 0, v[224:225]
	s_lshl_b32 s42, s57, 1
	v_lshl_add_u64 v[224:225], v[224:225], 0, s[42:43]
	s_lshl_b32 s42, s92, 1
	v_lshl_add_u64 v[224:225], v[224:225], 0, s[42:43]
	v_lshl_add_u64 v[224:225], v[224:225], 0, v[232:233]
	s_movk_i32 s42, 0x1000
	v_lshl_add_u64 v[220:221], v[224:225], 0, s[42:43]
	s_waitcnt lgkmcnt(0)
	s_barrier
	s_branch .LBB0_410

.LBB0_412:
	s_cmp_lg_u32 s93, 0
	s_cselect_b64 s[12:13], -1, 0
	s_and_b64 s[50:51], s[12:13], s[4:5]
	s_and_saveexec_b64 s[12:13], s[50:51]
	s_cbranch_execz .LBB0_414
	s_add_i32 s42, s93, -1
	s_lshl_b32 s50, s42, 14
	s_and_b32 s50, s50, 0x4000
	v_add_u32_e32 v134, s50, v222
	ds_read_b128 v[116:119], v134 offset:45056
	ds_read_b128 v[120:123], v134 offset:46080
	ds_read_b128 v[124:127], v134 offset:47104
	ds_read_b128 v[24:27], v134 offset:48128
	s_mov_b32 s42, 0x8000
	v_lshl_add_u64 v[220:221], v[220:221], 0, s[42:43]
	v_and_b32_e32 v135, 15, v152
	v_mov_b32_e32 v130, 0
	v_mov_b32_e32 v131, 0x3c00
	v_cmp_eq_u32_e32 vcc, 0, v135
	v_mov_b32_e32 v132, 0x3c000000
	s_nop 1
	v_cndmask_b32_e32 v130, v130, v131, vcc
	v_cmp_eq_u32_e32 vcc, 1, v135
	s_nop 1
	v_cndmask_b32_e32 v130, v130, v132, vcc
	s_nop 0
	v_mov_b32_e32 v131, v130
	v_mov_b32_e32 v132, v130
	v_mov_b32_e32 v133, v130
	s_nop 1
	s_waitcnt lgkmcnt(3)
	v_mfma_f32_16x16x32_f16 v[28:31], v[130:133], v[116:119], 0
	s_waitcnt lgkmcnt(2)
	v_mfma_f32_16x16x32_f16 v[32:35], v[130:133], v[120:123], 0
	s_waitcnt lgkmcnt(1)
	v_mfma_f32_16x16x32_f16 v[116:119], v[130:133], v[124:127], 0
	s_waitcnt lgkmcnt(0)
	v_mfma_f32_16x16x32_f16 v[120:123], v[130:133], v[24:27], 0
	s_mov_b64 s[50:51], exec
	s_nop 7
	v_cvt_pk_f16_f32 v28, v28, v29
	v_cvt_pk_f16_f32 v32, v32, v33
	v_cvt_pk_f16_f32 v116, v116, v117
	v_cvt_pk_f16_f32 v120, v120, v121
	s_mov_b64 exec, 0xffff
	global_store_dword v[220:221], v28, off offset:-4096
	global_store_dword v[220:221], v32, off offset:-2048
	global_store_dword v[220:221], v116, off
	global_store_dword v[220:221], v120, off offset:2048
	s_mov_b64 exec, s[50:51]

.LBB0_423:
	s_and_saveexec_b64 s[12:13], s[4:5]
	s_cbranch_execz .LBB0_425
	s_mulk_i32 s42, 0xe800
	s_add_i32 s97, s97, s42
	v_add_u32_e32 v134, s97, v222
	ds_read_b128 v[116:119], v134 offset:45056
	ds_read_b128 v[120:123], v134 offset:46080
	ds_read_b128 v[124:127], v134 offset:47104
	ds_read_b128 v[28:31], v134 offset:48128
	s_mov_b32 s42, 0x8000
	v_lshl_add_u64 v[220:221], v[220:221], 0, s[42:43]
	v_and_b32_e32 v135, 15, v152
	v_mov_b32_e32 v130, 0
	v_mov_b32_e32 v131, 0x3c00
	v_cmp_eq_u32_e32 vcc, 0, v135
	v_mov_b32_e32 v132, 0x3c000000
	s_nop 1
	v_cndmask_b32_e32 v130, v130, v131, vcc
	v_cmp_eq_u32_e32 vcc, 1, v135
	s_nop 1
	v_cndmask_b32_e32 v130, v130, v132, vcc
	s_nop 0
	v_mov_b32_e32 v131, v130
	v_mov_b32_e32 v132, v130
	v_mov_b32_e32 v133, v130
	s_nop 1
	s_waitcnt lgkmcnt(3)
	v_mfma_f32_16x16x32_f16 v[90:93], v[130:133], v[116:119], 0
	s_waitcnt lgkmcnt(2)
	v_mfma_f32_16x16x32_f16 v[32:35], v[130:133], v[120:123], 0
	s_waitcnt lgkmcnt(1)
	v_mfma_f32_16x16x32_f16 v[116:119], v[130:133], v[124:127], 0
	s_waitcnt lgkmcnt(0)
	v_mfma_f32_16x16x32_f16 v[120:123], v[130:133], v[28:31], 0
	s_mov_b64 s[50:51], exec
	s_nop 7
	v_cvt_pk_f16_f32 v90, v90, v91
	v_cvt_pk_f16_f32 v32, v32, v33
	v_cvt_pk_f16_f32 v116, v116, v117
	v_cvt_pk_f16_f32 v120, v120, v121
	s_mov_b64 exec, 0xffff
	global_store_dword v[220:221], v90, off offset:-4096
	global_store_dword v[220:221], v32, off offset:-2048
	global_store_dword v[220:221], v116, off
	global_store_dword v[220:221], v120, off offset:2048
	s_mov_b64 exec, s[50:51]

.LBB0_434:
	s_and_saveexec_b64 s[12:13], s[4:5]
	s_cbranch_execz .LBB0_436
	s_lshl_b32 s42, s96, 14
	s_and_b32 s42, s42, 0x4000
	v_add_u32_e32 v134, s42, v222
	ds_read_b128 v[116:119], v134 offset:45056
	ds_read_b128 v[120:123], v134 offset:46080
	ds_read_b128 v[124:127], v134 offset:47104
	ds_read_b128 v[20:23], v134 offset:48128
	s_mov_b32 s42, 0x8000
	v_lshl_add_u64 v[220:221], v[220:221], 0, s[42:43]
	v_and_b32_e32 v135, 15, v152
	v_mov_b32_e32 v130, 0
	v_mov_b32_e32 v131, 0x3c00
	v_cmp_eq_u32_e32 vcc, 0, v135
	v_mov_b32_e32 v132, 0x3c000000
	s_nop 1
	v_cndmask_b32_e32 v130, v130, v131, vcc
	v_cmp_eq_u32_e32 vcc, 1, v135
	s_nop 1
	v_cndmask_b32_e32 v130, v130, v132, vcc
	s_nop 0
	v_mov_b32_e32 v131, v130
	v_mov_b32_e32 v132, v130
	v_mov_b32_e32 v133, v130
	s_nop 1
	s_waitcnt lgkmcnt(3)
	v_mfma_f32_16x16x32_f16 v[24:27], v[130:133], v[116:119], 0
	s_waitcnt lgkmcnt(2)
	v_mfma_f32_16x16x32_f16 v[92:95], v[130:133], v[120:123], 0
	s_waitcnt lgkmcnt(1)
	v_mfma_f32_16x16x32_f16 v[116:119], v[130:133], v[124:127], 0
	s_waitcnt lgkmcnt(0)
	v_mfma_f32_16x16x32_f16 v[120:123], v[130:133], v[20:23], 0
	s_mov_b64 s[50:51], exec
	s_nop 7
	v_cvt_pk_f16_f32 v24, v24, v25
	v_cvt_pk_f16_f32 v92, v92, v93
	v_cvt_pk_f16_f32 v116, v116, v117
	v_cvt_pk_f16_f32 v120, v120, v121
	s_mov_b64 exec, 0xffff
	global_store_dword v[220:221], v24, off offset:-4096
	global_store_dword v[220:221], v92, off offset:-2048
	global_store_dword v[220:221], v116, off
	global_store_dword v[220:221], v120, off offset:2048
	s_mov_b64 exec, s[50:51]
